# sgemm loads reordered so both 64B halves of each 128B line are adjacent (k-pair order); full-unit tile ring
# speedup vs baseline: 1.0621x; 1.0019x over previous
.LBB0_475:
	v_lshl_add_u64 v[76:77], v[62:63], 0, s[28:29]
	v_lshl_add_u64 v[78:79], v[64:65], 0, s[28:29]
	v_add_co_u32_e32 v80, vcc, s89, v78
	s_nop 1
	v_addc_co_u32_e32 v81, vcc, 0, v79, vcc
	v_add_co_u32_e32 v82, vcc, s96, v78
	s_nop 1
	v_addc_co_u32_e32 v83, vcc, 0, v79, vcc
	v_add_co_u32_e32 v84, vcc, s71, v78
	s_nop 1
	v_addc_co_u32_e32 v85, vcc, 0, v79, vcc
	v_add_co_u32_e32 v86, vcc, s86, v78
	s_nop 1
	v_addc_co_u32_e32 v87, vcc, 0, v79, vcc
	v_add_co_u32_e32 v88, vcc, s88, v78
	s_nop 1
	v_addc_co_u32_e32 v89, vcc, 0, v79, vcc
	v_add_co_u32_e32 v90, vcc, s61, v78
	s_nop 1
	v_addc_co_u32_e32 v91, vcc, 0, v79, vcc
	v_add_co_u32_e32 v92, vcc, s65, v78
	s_nop 1
	v_addc_co_u32_e32 v93, vcc, 0, v79, vcc
	v_add_co_u32_e32 v78, vcc, s64, v78
	s_nop 1
	v_addc_co_u32_e32 v79, vcc, 0, v79, vcc
	global_load_dwordx4 v[118:121], v[76:77], off
	global_load_dwordx4 v[122:125], v[76:77], off offset:64
	global_load_dwordx4 v[126:129], v[76:77], off offset:128
	global_load_dwordx4 v[130:133], v[76:77], off offset:192
	global_load_dwordx4 v[134:137], v[80:81], off
	global_load_dwordx4 v[138:141], v[80:81], off offset:64
	global_load_dwordx4 v[142:145], v[82:83], off
	global_load_dwordx4 v[146:149], v[82:83], off offset:64
	global_load_dwordx4 v[150:153], v[84:85], off
	global_load_dwordx4 v[154:157], v[84:85], off offset:64
	global_load_dwordx4 v[158:161], v[86:87], off
	global_load_dwordx4 v[162:165], v[86:87], off offset:64
	global_load_dwordx4 v[166:169], v[88:89], off
	global_load_dwordx4 v[182:185], v[88:89], off offset:64
	global_load_dwordx4 v[186:189], v[90:91], off
	global_load_dwordx4 v[190:193], v[90:91], off offset:64
	global_load_dwordx4 v[194:197], v[92:93], off
	global_load_dwordx4 v[202:205], v[92:93], off offset:64
	global_load_dwordx4 v[206:209], v[78:79], off
	global_load_dwordx4 v[210:213], v[78:79], off offset:64
	global_load_dwordx4 v[214:217], v[80:81], off offset:128
	global_load_dwordx4 v[220:223], v[80:81], off offset:192
	global_load_dwordx4 v[224:227], v[82:83], off offset:128
	global_load_dwordx4 v[228:231], v[82:83], off offset:192
	global_load_dwordx4 v[232:235], v[84:85], off offset:128
	global_load_dwordx4 v[244:247], v[84:85], off offset:192
	s_waitcnt vmcnt(20)
	v_mfma_f32_16x16x32_bf16 v[36:39], v[118:121], v[134:137], v[36:39]
	v_mfma_f32_16x16x32_bf16 v[36:39], v[122:125], v[138:141], v[36:39]
	global_load_dwordx4 v[134:137], v[86:87], off offset:128
	global_load_dwordx4 v[138:141], v[86:87], off offset:192
	s_waitcnt vmcnt(20)
	v_mfma_f32_16x16x32_bf16 v[32:35], v[118:121], v[142:145], v[32:35]
	v_mfma_f32_16x16x32_bf16 v[32:35], v[122:125], v[146:149], v[32:35]
	global_load_dwordx4 v[142:145], v[88:89], off offset:128
	global_load_dwordx4 v[146:149], v[88:89], off offset:192
	s_waitcnt vmcnt(20)
	v_mfma_f32_16x16x32_bf16 v[28:31], v[118:121], v[150:153], v[28:31]
	v_mfma_f32_16x16x32_bf16 v[28:31], v[122:125], v[154:157], v[28:31]
	global_load_dwordx4 v[150:153], v[90:91], off offset:128
	global_load_dwordx4 v[154:157], v[90:91], off offset:192
	s_waitcnt vmcnt(20)
	v_mfma_f32_16x16x32_bf16 v[24:27], v[118:121], v[158:161], v[24:27]
	v_mfma_f32_16x16x32_bf16 v[24:27], v[122:125], v[162:165], v[24:27]
	global_load_dwordx4 v[158:161], v[92:93], off offset:128
	global_load_dwordx4 v[162:165], v[92:93], off offset:192
	s_waitcnt vmcnt(20)
	v_mfma_f32_16x16x32_bf16 v[20:23], v[118:121], v[166:169], v[20:23]
	v_mfma_f32_16x16x32_bf16 v[20:23], v[122:125], v[182:185], v[20:23]
	global_load_dwordx4 v[166:169], v[78:79], off offset:128
	global_load_dwordx4 v[182:185], v[78:79], off offset:192
	s_waitcnt vmcnt(20)
	v_mfma_f32_16x16x32_bf16 v[16:19], v[118:121], v[186:189], v[16:19]
	v_mfma_f32_16x16x32_bf16 v[16:19], v[122:125], v[190:193], v[16:19]
	s_waitcnt vmcnt(18)
	v_mfma_f32_16x16x32_bf16 v[12:15], v[118:121], v[194:197], v[12:15]
	v_mfma_f32_16x16x32_bf16 v[12:15], v[122:125], v[202:205], v[12:15]
	s_waitcnt vmcnt(16)
	v_mfma_f32_16x16x32_bf16 v[8:11], v[118:121], v[206:209], v[8:11]
	v_mfma_f32_16x16x32_bf16 v[8:11], v[122:125], v[210:213], v[8:11]
	s_waitcnt vmcnt(14)
	v_mfma_f32_16x16x32_bf16 v[36:39], v[126:129], v[214:217], v[36:39]
	v_mfma_f32_16x16x32_bf16 v[36:39], v[130:133], v[220:223], v[36:39]
	s_waitcnt vmcnt(12)
	v_mfma_f32_16x16x32_bf16 v[32:35], v[126:129], v[224:227], v[32:35]
	v_mfma_f32_16x16x32_bf16 v[32:35], v[130:133], v[228:231], v[32:35]
	s_waitcnt vmcnt(10)
	v_mfma_f32_16x16x32_bf16 v[28:31], v[126:129], v[232:235], v[28:31]
	v_mfma_f32_16x16x32_bf16 v[28:31], v[130:133], v[244:247], v[28:31]
	s_waitcnt vmcnt(8)
	v_mfma_f32_16x16x32_bf16 v[24:27], v[126:129], v[134:137], v[24:27]
	v_mfma_f32_16x16x32_bf16 v[24:27], v[130:133], v[138:141], v[24:27]
	s_waitcnt vmcnt(6)
	v_mfma_f32_16x16x32_bf16 v[20:23], v[126:129], v[142:145], v[20:23]
	v_mfma_f32_16x16x32_bf16 v[20:23], v[130:133], v[146:149], v[20:23]
	s_waitcnt vmcnt(4)
	v_mfma_f32_16x16x32_bf16 v[16:19], v[126:129], v[150:153], v[16:19]
	v_mfma_f32_16x16x32_bf16 v[16:19], v[130:133], v[154:157], v[16:19]
	s_waitcnt vmcnt(2)
	v_mfma_f32_16x16x32_bf16 v[12:15], v[126:129], v[158:161], v[12:15]
	v_mfma_f32_16x16x32_bf16 v[12:15], v[130:133], v[162:165], v[12:15]
	s_waitcnt vmcnt(0)
	v_mfma_f32_16x16x32_bf16 v[8:11], v[126:129], v[166:169], v[8:11]
	v_mfma_f32_16x16x32_bf16 v[8:11], v[130:133], v[182:185], v[8:11]
	s_nop 4
	v_add_u32_e32 v55, s20, v61
	ds_write_b128 v55, v[36:39]
	ds_write_b128 v55, v[32:35] offset:1024
	ds_write_b128 v55, v[28:31] offset:2048
	ds_write_b128 v55, v[24:27] offset:3072
	ds_write_b128 v55, v[20:23] offset:4096
	ds_write_b128 v55, v[16:19] offset:5120
	ds_write_b128 v55, v[12:15] offset:6144
	ds_write_b128 v55, v[8:11] offset:7168
	v_add_u32_e32 v24, s21, v61
	s_waitcnt lgkmcnt(0)
	s_barrier
	ds_read_b128 v[8:11], v24
	ds_read_b128 v[12:15], v24 offset:8192
	ds_read_b128 v[16:19], v24 offset:16384
	v_xor_b32_e32 v7, 0x80000000, v7
	v_xor_b32_e32 v6, 0x80000000, v6
	s_waitcnt lgkmcnt(2)
	v_pk_add_f32 v[10:11], v[10:11], 0 op_sel_hi:[1,0]
	v_pk_add_f32 v[20:21], v[8:9], 0 op_sel_hi:[1,0]
	s_waitcnt lgkmcnt(1)
	v_pk_add_f32 v[14:15], v[10:11], v[14:15]
	ds_read_b128 v[8:11], v24 offset:24576
	v_pk_add_f32 v[20:21], v[20:21], v[12:13]
	s_waitcnt lgkmcnt(1)
	v_pk_add_f32 v[18:19], v[14:15], v[18:19]
	ds_read_b128 v[12:15], v24 offset:32768
	v_pk_add_f32 v[16:17], v[20:21], v[16:17]
	s_waitcnt lgkmcnt(1)
	v_pk_add_f32 v[18:19], v[18:19], v[10:11]
	v_pk_add_f32 v[20:21], v[16:17], v[8:9]
	ds_read_b128 v[8:11], v24 offset:40960
	s_waitcnt lgkmcnt(1)
	v_pk_add_f32 v[22:23], v[18:19], v[14:15]
	ds_read_b128 v[14:17], v24 offset:49152
	v_pk_add_f32 v[12:13], v[20:21], v[12:13]
	ds_read_b128 v[18:21], v24 offset:57344
	s_waitcnt lgkmcnt(2)
	v_pk_add_f32 v[10:11], v[22:23], v[10:11]
	v_pk_add_f32 v[8:9], v[12:13], v[8:9]
	s_waitcnt lgkmcnt(1)
	v_pk_add_f32 v[10:11], v[10:11], v[16:17]
	v_pk_add_f32 v[8:9], v[8:9], v[14:15]
	s_waitcnt lgkmcnt(0)
	v_pk_add_f32 v[10:11], v[10:11], v[20:21]
	v_pk_add_f32 v[8:9], v[8:9], v[18:19]
	v_pk_fma_f32 v[6:7], v[6:7], v[58:59], v[10:11] op_sel_hi:[1,0,1]
	v_pk_fma_f32 v[4:5], v[4:5], v[58:59], v[8:9] op_sel_hi:[1,0,1] neg_lo:[1,0,0] neg_hi:[1,0,0]
	v_pk_fma_f32 v[2:3], v[60:61], v[6:7], v[2:3] op_sel_hi:[0,1,1]
	v_pk_fma_f32 v[0:1], v[60:61], v[4:5], v[0:1] op_sel_hi:[0,1,1]
	v_cndmask_b32_e64 v3, v3, v11, s[22:23]
	v_cndmask_b32_e64 v2, v2, v10, s[22:23]
	v_cndmask_b32_e64 v1, v1, v9, s[22:23]
	v_cndmask_b32_e64 v0, v0, v8, s[22:23]
	v_cmp_lt_i32_e32 vcc, s19, v56
	s_and_saveexec_b64 s[10:11], vcc
	s_xor_b64 s[10:11], exec, s[10:11]
	s_cbranch_execz .LBB0_485
	s_cmpk_gt_u32 s4, 0x2ff
	s_mov_b64 s[12:13], -1
	s_cbranch_scc0 .LBB0_479
	v_lshl_add_u64 v[4:5], v[56:57], 1, v[42:43]
	v_add_co_u32_e32 v4, vcc, 0x82af000, v4
	v_cvt_pk_bf16_f32 v6, v0, v1
	v_cvt_pk_bf16_f32 v7, v2, v3
	s_mov_b64 s[12:13], 0
	s_nop 0
	v_addc_co_u32_e32 v5, vcc, 0, v5, vcc
	global_store_dwordx2 v[4:5], v[6:7], off offset:2560

.LBB0_1096:
	v_lshl_add_u64 v[66:67], v[60:61], 0, s[42:43]
	s_mov_b32 s11, 0x600000
	v_add_co_u32_e32 v74, vcc, s11, v66
	v_lshl_add_u64 v[76:77], v[62:63], 0, s[42:43]
	s_nop 1
	v_addc_co_u32_e32 v75, vcc, 0, v67, vcc
	s_lshl_b32 s10, s101, 16
	s_mov_b32 s11, 0
	v_lshl_add_u64 v[76:77], v[76:77], 0, s[10:11]
	v_add_co_u32_e32 v78, vcc, s52, v76
	s_mov_b32 s11, 0x6a48000
	s_nop 1
	v_addc_co_u32_e32 v79, vcc, 0, v77, vcc
	v_add_co_u32_e32 v80, vcc, s11, v76
	s_nop 1
	v_addc_co_u32_e32 v81, vcc, 0, v77, vcc
	global_load_dwordx4 v[118:121], v[74:75], off
	global_load_dwordx4 v[122:125], v[74:75], off offset:64
	global_load_dwordx4 v[126:129], v[78:79], off
	global_load_dwordx4 v[130:133], v[78:79], off offset:64
	global_load_dwordx4 v[134:137], v[80:81], off
	global_load_dwordx4 v[138:141], v[80:81], off offset:64
	global_load_dwordx4 v[142:145], v[74:75], off offset:128
	global_load_dwordx4 v[146:149], v[74:75], off offset:192
	global_load_dwordx4 v[150:153], v[78:79], off offset:128
	global_load_dwordx4 v[154:157], v[78:79], off offset:192
	global_load_dwordx4 v[158:161], v[80:81], off offset:128
	global_load_dwordx4 v[162:165], v[80:81], off offset:192
	s_waitcnt vmcnt(6)
	v_mfma_f32_16x16x32_bf16 v[36:39], v[118:121], v[126:129], v[36:39]
	v_mfma_f32_16x16x32_bf16 v[32:35], v[118:121], v[134:137], v[32:35]
	v_mfma_f32_16x16x32_bf16 v[36:39], v[122:125], v[130:133], v[36:39]
	v_mfma_f32_16x16x32_bf16 v[32:35], v[122:125], v[138:141], v[32:35]
	s_waitcnt vmcnt(0)
	v_mfma_f32_16x16x32_bf16 v[36:39], v[142:145], v[150:153], v[36:39]
	v_mfma_f32_16x16x32_bf16 v[32:35], v[142:145], v[158:161], v[32:35]
	v_mfma_f32_16x16x32_bf16 v[36:39], v[146:149], v[154:157], v[36:39]
	v_mfma_f32_16x16x32_bf16 v[32:35], v[146:149], v[162:165], v[32:35]
	s_nop 4
	v_add_u32_e32 v49, s4, v55
	v_lshl_add_u32 v49, s101, 11, v49
	ds_write_b128 v49, v[36:39]
	ds_write_b128 v49, v[32:35] offset:1024
	v_add_u32_e32 v24, s12, v55
	s_waitcnt lgkmcnt(0)
	s_barrier
	s_lshr_b32 s10, s12, 11
	s_cmp_lg_u32 s10, s101
	s_cbranch_scc1 .LBB0_1092
	ds_read_b128 v[8:11], v24
	ds_read_b128 v[12:15], v24 offset:8192
	ds_read_b128 v[16:19], v24 offset:16384
	s_waitcnt lgkmcnt(2)
	v_pk_add_f32 v[10:11], v[10:11], 0 op_sel_hi:[1,0]
	v_pk_add_f32 v[20:21], v[8:9], 0 op_sel_hi:[1,0]
	s_waitcnt lgkmcnt(1)
	v_pk_add_f32 v[14:15], v[10:11], v[14:15]
	ds_read_b128 v[8:11], v24 offset:24576
	v_pk_add_f32 v[20:21], v[20:21], v[12:13]
	s_waitcnt lgkmcnt(1)
	v_pk_add_f32 v[18:19], v[14:15], v[18:19]
	ds_read_b128 v[12:15], v24 offset:32768
	v_pk_add_f32 v[16:17], v[20:21], v[16:17]
	s_waitcnt lgkmcnt(1)
	v_pk_add_f32 v[18:19], v[18:19], v[10:11]
	v_pk_add_f32 v[20:21], v[16:17], v[8:9]
	ds_read_b128 v[8:11], v24 offset:40960
	s_waitcnt lgkmcnt(1)
	v_pk_add_f32 v[22:23], v[18:19], v[14:15]
	ds_read_b128 v[14:17], v24 offset:49152
	v_pk_add_f32 v[12:13], v[20:21], v[12:13]
	ds_read_b128 v[18:21], v24 offset:57344
	s_waitcnt lgkmcnt(2)
	v_pk_add_f32 v[8:9], v[12:13], v[8:9]
	v_pk_add_f32 v[10:11], v[22:23], v[10:11]
	s_waitcnt lgkmcnt(1)
	v_pk_add_f32 v[8:9], v[8:9], v[14:15]
	v_pk_add_f32 v[10:11], v[10:11], v[16:17]
	s_waitcnt lgkmcnt(0)
	v_pk_add_f32 v[8:9], v[8:9], v[18:19]
	v_lshlrev_b32_e32 v18, 16, v59
	v_and_b32_e32 v19, 0xffff0000, v59
	v_lshlrev_b32_e32 v16, 16, v58
	v_and_b32_e32 v17, 0xffff0000, v58
	v_sub_f32_e32 v13, v19, v56
	v_sub_f32_e32 v12, v18, v56
	v_sub_f32_e32 v15, v17, v56
	v_sub_f32_e32 v14, v16, v56
	v_pk_mul_f32 v[12:13], v[54:55], v[12:13] op_sel_hi:[0,1]
	v_pk_mul_f32 v[14:15], v[54:55], v[14:15] op_sel_hi:[0,1]
	v_pk_fma_f32 v[2:3], v[2:3], v[12:13], v[6:7]
	v_pk_add_f32 v[10:11], v[10:11], v[20:21]
	v_pk_fma_f32 v[0:1], v[0:1], v[14:15], v[4:5]
	v_cndmask_b32_e64 v3, v3, v19, s[28:29]
	v_cndmask_b32_e64 v2, v2, v18, s[28:29]
	v_cndmask_b32_e64 v1, v1, v17, s[28:29]
	v_cndmask_b32_e64 v0, v0, v16, s[28:29]
	v_pk_fma_f32 v[4:5], v[2:3], s[70:71], v[10:11] op_sel_hi:[1,0,1]
	v_and_b32_e32 v2, 64, v237
	v_pk_fma_f32 v[6:7], v[0:1], s[70:71], v[8:9] op_sel_hi:[1,0,1]
	v_xor_b32_e32 v0, 16, v237
	v_add_u32_e32 v12, 64, v2
	v_cmp_lt_i32_e32 vcc, v0, v12
	v_mul_f32_e32 v1, v6, v6
	v_mul_f32_e32 v3, v7, v7
	v_cndmask_b32_e32 v0, v237, v0, vcc
	v_mul_f32_e32 v9, v4, v4
	v_mul_f32_e32 v11, v5, v5
	v_lshlrev_b32_e32 v13, 2, v0
	v_mov_b32_e32 v0, v6
	v_mov_b32_e32 v2, v7
	v_mov_b32_e32 v8, v4
	v_mov_b32_e32 v10, v5
	v_pk_add_f32 v[0:1], v[0:1], v[2:3]
	v_pk_add_f32 v[2:3], v[8:9], v[10:11]
	v_xor_b32_e32 v8, 32, v237
	v_pk_add_f32 v[0:1], v[0:1], v[2:3]
	ds_bpermute_b32 v2, v13, v0
	ds_bpermute_b32 v3, v13, v1
	v_cmp_lt_i32_e32 vcc, v8, v12
	v_cvt_pk_bf16_f32 v6, v6, v7
	v_cvt_pk_bf16_f32 v7, v4, v5
	global_store_dwordx2 v[52:53], v[6:7], off
	s_waitcnt lgkmcnt(0)
	v_pk_add_f32 v[0:1], v[0:1], v[2:3]
	v_cndmask_b32_e32 v8, v237, v8, vcc
	v_lshlrev_b32_e32 v8, 2, v8
	ds_bpermute_b32 v2, v8, v0
	ds_bpermute_b32 v3, v8, v1
	s_and_saveexec_b64 s[10:11], s[30:31]
	s_cbranch_execz .LBB0_1092
	s_lshl_b32 s16, s100, 1
	s_ashr_i32 s17, s16, 31
	v_lshl_add_u64 v[4:5], s[16:17], 2, v[44:45]
	s_waitcnt lgkmcnt(0)
	v_pk_add_f32 v[0:1], v[0:1], v[2:3]
	global_store_dwordx2 v[4:5], v[0:1], off
	s_branch .LBB0_1092

.LBB0_1271:
	v_lshl_add_u64 v[92:93], v[82:83], 0, s[28:29]
	s_mov_b32 s13, 0xa00000
	v_add_co_u32_e32 v100, vcc, s13, v92
	v_lshl_add_u64 v[102:103], v[86:87], 0, s[28:29]
	s_nop 1
	v_addc_co_u32_e32 v101, vcc, 0, v93, vcc
	v_add_co_u32_e32 v104, vcc, s89, v102
	s_nop 1
	v_addc_co_u32_e32 v105, vcc, 0, v103, vcc
	v_add_co_u32_e32 v106, vcc, s96, v102
	s_nop 1
	v_addc_co_u32_e32 v107, vcc, 0, v103, vcc
	v_add_co_u32_e32 v108, vcc, s71, v102
	s_nop 1
	v_addc_co_u32_e32 v109, vcc, 0, v103, vcc
	v_add_co_u32_e32 v110, vcc, s86, v102
	s_nop 1
	v_addc_co_u32_e32 v111, vcc, 0, v103, vcc
	v_add_co_u32_e32 v112, vcc, s88, v102
	s_nop 1
	v_addc_co_u32_e32 v113, vcc, 0, v103, vcc
	v_add_co_u32_e32 v114, vcc, s61, v102
	s_nop 1
	v_addc_co_u32_e32 v115, vcc, 0, v103, vcc
	v_add_co_u32_e32 v116, vcc, s65, v102
	s_nop 1
	v_addc_co_u32_e32 v117, vcc, 0, v103, vcc
	v_add_co_u32_e32 v102, vcc, s64, v102
	s_nop 1
	v_addc_co_u32_e32 v103, vcc, 0, v103, vcc
	global_load_dwordx4 v[118:121], v[100:101], off
	global_load_dwordx4 v[122:125], v[100:101], off offset:64
	global_load_dwordx4 v[126:129], v[100:101], off offset:128
	global_load_dwordx4 v[130:133], v[100:101], off offset:192
	global_load_dwordx4 v[134:137], v[104:105], off
	global_load_dwordx4 v[138:141], v[104:105], off offset:64
	global_load_dwordx4 v[142:145], v[106:107], off
	global_load_dwordx4 v[146:149], v[106:107], off offset:64
	global_load_dwordx4 v[150:153], v[108:109], off
	global_load_dwordx4 v[154:157], v[108:109], off offset:64
	global_load_dwordx4 v[158:161], v[110:111], off
	global_load_dwordx4 v[162:165], v[110:111], off offset:64
	global_load_dwordx4 v[166:169], v[112:113], off
	global_load_dwordx4 v[182:185], v[112:113], off offset:64
	global_load_dwordx4 v[186:189], v[114:115], off
	global_load_dwordx4 v[190:193], v[114:115], off offset:64
	global_load_dwordx4 v[194:197], v[116:117], off
	global_load_dwordx4 v[202:205], v[116:117], off offset:64
	global_load_dwordx4 v[206:209], v[102:103], off
	global_load_dwordx4 v[210:213], v[102:103], off offset:64
	global_load_dwordx4 v[214:217], v[104:105], off offset:128
	global_load_dwordx4 v[220:223], v[104:105], off offset:192
	global_load_dwordx4 v[224:227], v[106:107], off offset:128
	global_load_dwordx4 v[228:231], v[106:107], off offset:192
	global_load_dwordx4 v[232:235], v[108:109], off offset:128
	global_load_dwordx4 v[244:247], v[108:109], off offset:192
	s_waitcnt vmcnt(20)
	v_mfma_f32_16x16x32_bf16 v[64:67], v[118:121], v[134:137], v[64:67]
	v_mfma_f32_16x16x32_bf16 v[64:67], v[122:125], v[138:141], v[64:67]
	global_load_dwordx4 v[134:137], v[110:111], off offset:128
	global_load_dwordx4 v[138:141], v[110:111], off offset:192
	s_waitcnt vmcnt(20)
	v_mfma_f32_16x16x32_bf16 v[60:63], v[118:121], v[142:145], v[60:63]
	v_mfma_f32_16x16x32_bf16 v[60:63], v[122:125], v[146:149], v[60:63]
	global_load_dwordx4 v[142:145], v[112:113], off offset:128
	global_load_dwordx4 v[146:149], v[112:113], off offset:192
	s_waitcnt vmcnt(20)
	v_mfma_f32_16x16x32_bf16 v[56:59], v[118:121], v[150:153], v[56:59]
	v_mfma_f32_16x16x32_bf16 v[56:59], v[122:125], v[154:157], v[56:59]
	global_load_dwordx4 v[150:153], v[114:115], off offset:128
	global_load_dwordx4 v[154:157], v[114:115], off offset:192
	s_waitcnt vmcnt(20)
	v_mfma_f32_16x16x32_bf16 v[52:55], v[118:121], v[158:161], v[52:55]
	v_mfma_f32_16x16x32_bf16 v[52:55], v[122:125], v[162:165], v[52:55]
	global_load_dwordx4 v[158:161], v[116:117], off offset:128
	global_load_dwordx4 v[162:165], v[116:117], off offset:192
	s_waitcnt vmcnt(20)
	v_mfma_f32_16x16x32_bf16 v[48:51], v[118:121], v[166:169], v[48:51]
	v_mfma_f32_16x16x32_bf16 v[48:51], v[122:125], v[182:185], v[48:51]
	global_load_dwordx4 v[166:169], v[102:103], off offset:128
	global_load_dwordx4 v[182:185], v[102:103], off offset:192
	s_waitcnt vmcnt(20)
	v_mfma_f32_16x16x32_bf16 v[44:47], v[118:121], v[186:189], v[44:47]
	v_mfma_f32_16x16x32_bf16 v[44:47], v[122:125], v[190:193], v[44:47]
	s_waitcnt vmcnt(18)
	v_mfma_f32_16x16x32_bf16 v[68:71], v[118:121], v[194:197], v[68:71]
	v_mfma_f32_16x16x32_bf16 v[68:71], v[122:125], v[202:205], v[68:71]
	s_waitcnt vmcnt(16)
	v_mfma_f32_16x16x32_bf16 v[28:31], v[118:121], v[206:209], v[28:31]
	v_mfma_f32_16x16x32_bf16 v[28:31], v[122:125], v[210:213], v[28:31]
	s_waitcnt vmcnt(14)
	v_mfma_f32_16x16x32_bf16 v[64:67], v[126:129], v[214:217], v[64:67]
	v_mfma_f32_16x16x32_bf16 v[64:67], v[130:133], v[220:223], v[64:67]
	s_waitcnt vmcnt(12)
	v_mfma_f32_16x16x32_bf16 v[60:63], v[126:129], v[224:227], v[60:63]
	v_mfma_f32_16x16x32_bf16 v[60:63], v[130:133], v[228:231], v[60:63]
	s_waitcnt vmcnt(10)
	v_mfma_f32_16x16x32_bf16 v[56:59], v[126:129], v[232:235], v[56:59]
	v_mfma_f32_16x16x32_bf16 v[56:59], v[130:133], v[244:247], v[56:59]
	s_waitcnt vmcnt(8)
	v_mfma_f32_16x16x32_bf16 v[52:55], v[126:129], v[134:137], v[52:55]
	v_mfma_f32_16x16x32_bf16 v[52:55], v[130:133], v[138:141], v[52:55]
	s_waitcnt vmcnt(6)
	v_mfma_f32_16x16x32_bf16 v[48:51], v[126:129], v[142:145], v[48:51]
	v_mfma_f32_16x16x32_bf16 v[48:51], v[130:133], v[146:149], v[48:51]
	s_waitcnt vmcnt(4)
	v_mfma_f32_16x16x32_bf16 v[44:47], v[126:129], v[150:153], v[44:47]
	v_mfma_f32_16x16x32_bf16 v[44:47], v[130:133], v[154:157], v[44:47]
	s_waitcnt vmcnt(2)
	v_mfma_f32_16x16x32_bf16 v[68:71], v[126:129], v[158:161], v[68:71]
	v_mfma_f32_16x16x32_bf16 v[68:71], v[130:133], v[162:165], v[68:71]
	s_waitcnt vmcnt(0)
	v_mfma_f32_16x16x32_bf16 v[28:31], v[126:129], v[166:169], v[28:31]
	v_mfma_f32_16x16x32_bf16 v[28:31], v[130:133], v[182:185], v[28:31]
	s_nop 4
	v_add_f32_e32 v4, v13, v15
	v_add_f32_e32 v6, v9, v11
	v_add_f32_e32 v4, 0, v4
	v_add_f32_e32 v5, v5, v7
	v_add_f32_e32 v4, v4, v6
	v_add_f32_e32 v1, v1, v3
	v_add_f32_e32 v4, v4, v5
	v_add_f32_e32 v3, v41, v43
	v_add_f32_e32 v1, v4, v1
	v_add_f32_e32 v7, v25, v27
	v_add_f32_e32 v1, v1, v3
	v_add_f32_e32 v8, v21, v23
	v_add_f32_e32 v1, v1, v7
	v_add_f32_e32 v9, v17, v19
	v_add_f32_e32 v1, v1, v8
	v_add_f32_e32 v8, v1, v9
	v_add_u32_e32 v1, s4, v88
	v_add_u32_e32 v18, s10, v88
	ds_bpermute_b32 v9, v89, v8
	ds_write_b128 v1, v[64:67]
	ds_write_b128 v1, v[60:63] offset:1024
	ds_write_b128 v1, v[56:59] offset:2048
	ds_write_b128 v1, v[52:55] offset:3072
	ds_write_b128 v1, v[48:51] offset:4096
	ds_write_b128 v1, v[44:47] offset:5120
	ds_write_b128 v1, v[68:71] offset:6144
	ds_write_b128 v1, v[28:31] offset:7168
	s_waitcnt lgkmcnt(0)
	s_barrier
	ds_read_b128 v[4:7], v18
	v_add_f32_e32 v13, v0, v2
	ds_read_b128 v[0:3], v18 offset:8192
	v_add_f32_e32 v12, v8, v9
	ds_bpermute_b32 v15, v90, v13
	s_waitcnt lgkmcnt(2)
	v_pk_add_f32 v[10:11], v[6:7], 0 op_sel_hi:[1,0]
	ds_read_b128 v[6:9], v18 offset:16384
	v_pk_add_f32 v[16:17], v[4:5], 0 op_sel_hi:[1,0]
	s_waitcnt lgkmcnt(2)
	v_pk_add_f32 v[10:11], v[10:11], v[2:3]
	ds_read_b128 v[2:5], v18 offset:24576
	v_pk_add_f32 v[0:1], v[16:17], v[0:1]
	s_waitcnt lgkmcnt(1)
	v_pk_add_f32 v[16:17], v[10:11], v[8:9]
	ds_read_b128 v[8:11], v18 offset:32768
	v_pk_add_f32 v[0:1], v[0:1], v[6:7]
	s_waitcnt lgkmcnt(1)
	v_pk_add_f32 v[4:5], v[16:17], v[4:5]
	v_pk_add_f32 v[6:7], v[0:1], v[2:3]
	ds_read_b128 v[0:3], v18 offset:40960
	s_waitcnt lgkmcnt(1)
	v_pk_add_f32 v[10:11], v[4:5], v[10:11]
	v_pk_add_f32 v[8:9], v[6:7], v[8:9]
	ds_read_b128 v[4:7], v18 offset:49152
	ds_bpermute_b32 v14, v90, v12
	s_waitcnt lgkmcnt(2)
	v_pk_add_f32 v[10:11], v[10:11], v[2:3]
	v_pk_add_f32 v[8:9], v[8:9], v[0:1]
	ds_read_b128 v[0:3], v18 offset:57344
	s_waitcnt lgkmcnt(2)
	v_pk_add_f32 v[6:7], v[10:11], v[6:7]
	s_waitcnt lgkmcnt(1)
	v_pk_add_f32 v[10:11], v[12:13], v[14:15]
	v_pk_add_f32 v[4:5], v[8:9], v[4:5]
	v_pk_mul_f32 v[10:11], v[10:11], s[6:7] op_sel_hi:[1,0]
	s_waitcnt lgkmcnt(0)
	v_pk_add_f32 v[0:1], v[4:5], v[0:1]
	v_fma_f32 v12, -v11, v11, v10
	v_max_f32_e32 v12, 0, v12
	v_add_f32_e32 v12, 0x3727c5ac, v12
	v_mul_f32_e32 v13, 0x4b800000, v12
	v_cmp_gt_f32_e32 vcc, s14, v12
	v_pk_add_f32 v[2:3], v[6:7], v[2:3]
	v_pk_fma_f32 v[0:1], v[32:33], v[10:11], v[0:1] op_sel:[0,1,0] neg_lo:[1,0,0] neg_hi:[1,0,0]
	v_cndmask_b32_e32 v12, v12, v13, vcc
	v_rsq_f32_e32 v12, v12
	v_xor_b32_e32 v7, 0x80000000, v35
	v_xor_b32_e32 v6, 0x80000000, v34
	v_pk_fma_f32 v[2:3], v[6:7], v[10:11], v[2:3] op_sel:[0,1,0]
	v_mul_f32_e32 v4, 0x45800000, v12
	v_cndmask_b32_e32 v4, v12, v4, vcc
	v_pk_fma_f32 v[0:1], v[0:1], v[4:5], v[36:37] op_sel_hi:[1,0,1]
	v_pk_fma_f32 v[2:3], v[2:3], v[4:5], v[38:39] op_sel_hi:[1,0,1]
	v_max_f32_e32 v0, 0, v0
	v_max_f32_e32 v1, 0, v1
	s_add_i32 s11, s11, s3
	v_max_f32_e32 v2, 0, v2
	v_max_f32_e32 v3, 0, v3
	v_pk_mul_f32 v[0:1], v[0:1], v[0:1]
	v_lshl_add_u64 v[4:5], v[84:85], 1, v[74:75]
	s_cmpk_lt_i32 s11, 0x100
	v_add_u32_e32 v78, s87, v78
	v_pk_mul_f32 v[2:3], v[2:3], v[2:3]
	v_cvt_pk_bf16_f32 v0, v0, v1
	s_nop 0
	v_cvt_pk_bf16_f32 v1, v2, v3
	global_store_dwordx2 v[4:5], v[0:1], off
	s_barrier
	s_cbranch_scc1 .LBB0_1270

.LBB0_1375:
	v_lshl_add_u64 v[68:69], v[52:53], 0, s[34:35]
	s_mov_b32 s11, 0x1a00000
	v_add_co_u32_e64 v76, s[22:23], s11, v68
	v_lshl_add_u64 v[78:79], v[62:63], 0, s[34:35]
	s_nop 1
	v_addc_co_u32_e64 v77, s[22:23], 0, v69, s[22:23]
	s_lshl_b32 s10, s101, 18
	s_mov_b32 s11, 0
	v_lshl_add_u64 v[78:79], v[78:79], 0, s[10:11]
	s_mov_b32 s11, 0xea80000
	v_add_co_u32_e64 v80, s[22:23], s11, v78
	s_mov_b32 s11, 0xeaa0000
	s_nop 1
	v_addc_co_u32_e64 v81, s[22:23], 0, v79, s[22:23]
	v_add_co_u32_e64 v82, s[22:23], s11, v78
	s_nop 1
	v_addc_co_u32_e64 v83, s[22:23], 0, v79, s[22:23]
	global_load_dwordx4 v[118:121], v[76:77], off
	global_load_dwordx4 v[122:125], v[76:77], off offset:64
	global_load_dwordx4 v[126:129], v[80:81], off
	global_load_dwordx4 v[130:133], v[80:81], off offset:64
	global_load_dwordx4 v[134:137], v[82:83], off
	global_load_dwordx4 v[138:141], v[82:83], off offset:64
	global_load_dwordx4 v[142:145], v[76:77], off offset:128
	global_load_dwordx4 v[146:149], v[76:77], off offset:192
	global_load_dwordx4 v[150:153], v[80:81], off offset:128
	global_load_dwordx4 v[154:157], v[80:81], off offset:192
	global_load_dwordx4 v[158:161], v[82:83], off offset:128
	global_load_dwordx4 v[162:165], v[82:83], off offset:192
	global_load_dwordx4 v[166:169], v[76:77], off offset:256
	global_load_dwordx4 v[182:185], v[76:77], off offset:320
	global_load_dwordx4 v[186:189], v[80:81], off offset:256
	global_load_dwordx4 v[190:193], v[80:81], off offset:320
	global_load_dwordx4 v[194:197], v[82:83], off offset:256
	global_load_dwordx4 v[202:205], v[82:83], off offset:320
	global_load_dwordx4 v[206:209], v[76:77], off offset:384
	global_load_dwordx4 v[210:213], v[76:77], off offset:448
	global_load_dwordx4 v[214:217], v[80:81], off offset:384
	global_load_dwordx4 v[220:223], v[80:81], off offset:448
	global_load_dwordx4 v[224:227], v[82:83], off offset:384
	global_load_dwordx4 v[228:231], v[82:83], off offset:448
	s_waitcnt vmcnt(18)
	v_mfma_f32_16x16x32_bf16 v[28:31], v[118:121], v[126:129], v[28:31]
	v_mfma_f32_16x16x32_bf16 v[24:27], v[118:121], v[134:137], v[24:27]
	v_mfma_f32_16x16x32_bf16 v[28:31], v[122:125], v[130:133], v[28:31]
	v_mfma_f32_16x16x32_bf16 v[24:27], v[122:125], v[138:141], v[24:27]
	global_load_dwordx4 v[118:121], v[76:77], off offset:512
	global_load_dwordx4 v[122:125], v[76:77], off offset:576
	global_load_dwordx4 v[126:129], v[80:81], off offset:512
	global_load_dwordx4 v[130:133], v[80:81], off offset:576
	global_load_dwordx4 v[134:137], v[82:83], off offset:512
	global_load_dwordx4 v[138:141], v[82:83], off offset:576
	s_waitcnt vmcnt(18)
	v_mfma_f32_16x16x32_bf16 v[28:31], v[142:145], v[150:153], v[28:31]
	v_mfma_f32_16x16x32_bf16 v[24:27], v[142:145], v[158:161], v[24:27]
	v_mfma_f32_16x16x32_bf16 v[28:31], v[146:149], v[154:157], v[28:31]
	v_mfma_f32_16x16x32_bf16 v[24:27], v[146:149], v[162:165], v[24:27]
	global_load_dwordx4 v[142:145], v[76:77], off offset:640
	global_load_dwordx4 v[146:149], v[76:77], off offset:704
	global_load_dwordx4 v[150:153], v[80:81], off offset:640
	global_load_dwordx4 v[154:157], v[80:81], off offset:704
	global_load_dwordx4 v[158:161], v[82:83], off offset:640
	global_load_dwordx4 v[162:165], v[82:83], off offset:704
	s_waitcnt vmcnt(18)
	v_mfma_f32_16x16x32_bf16 v[28:31], v[166:169], v[186:189], v[28:31]
	v_mfma_f32_16x16x32_bf16 v[24:27], v[166:169], v[194:197], v[24:27]
	v_mfma_f32_16x16x32_bf16 v[28:31], v[182:185], v[190:193], v[28:31]
	v_mfma_f32_16x16x32_bf16 v[24:27], v[182:185], v[202:205], v[24:27]
	global_load_dwordx4 v[166:169], v[76:77], off offset:768
	global_load_dwordx4 v[182:185], v[76:77], off offset:832
	global_load_dwordx4 v[186:189], v[80:81], off offset:768
	global_load_dwordx4 v[190:193], v[80:81], off offset:832
	global_load_dwordx4 v[194:197], v[82:83], off offset:768
	global_load_dwordx4 v[202:205], v[82:83], off offset:832
	s_waitcnt vmcnt(18)
	v_mfma_f32_16x16x32_bf16 v[28:31], v[206:209], v[214:217], v[28:31]
	v_mfma_f32_16x16x32_bf16 v[24:27], v[206:209], v[224:227], v[24:27]
	v_mfma_f32_16x16x32_bf16 v[28:31], v[210:213], v[220:223], v[28:31]
	v_mfma_f32_16x16x32_bf16 v[24:27], v[210:213], v[228:231], v[24:27]
	global_load_dwordx4 v[206:209], v[76:77], off offset:896
	global_load_dwordx4 v[210:213], v[76:77], off offset:960
	global_load_dwordx4 v[214:217], v[80:81], off offset:896
	global_load_dwordx4 v[220:223], v[80:81], off offset:960
	global_load_dwordx4 v[224:227], v[82:83], off offset:896
	global_load_dwordx4 v[228:231], v[82:83], off offset:960
	s_waitcnt vmcnt(18)
	v_mfma_f32_16x16x32_bf16 v[28:31], v[118:121], v[126:129], v[28:31]
	v_mfma_f32_16x16x32_bf16 v[24:27], v[118:121], v[134:137], v[24:27]
	v_mfma_f32_16x16x32_bf16 v[28:31], v[122:125], v[130:133], v[28:31]
	v_mfma_f32_16x16x32_bf16 v[24:27], v[122:125], v[138:141], v[24:27]
	s_waitcnt vmcnt(12)
	v_mfma_f32_16x16x32_bf16 v[28:31], v[142:145], v[150:153], v[28:31]
	v_mfma_f32_16x16x32_bf16 v[24:27], v[142:145], v[158:161], v[24:27]
	v_mfma_f32_16x16x32_bf16 v[28:31], v[146:149], v[154:157], v[28:31]
	v_mfma_f32_16x16x32_bf16 v[24:27], v[146:149], v[162:165], v[24:27]
	s_waitcnt vmcnt(6)
	v_mfma_f32_16x16x32_bf16 v[28:31], v[166:169], v[186:189], v[28:31]
	v_mfma_f32_16x16x32_bf16 v[24:27], v[166:169], v[194:197], v[24:27]
	v_mfma_f32_16x16x32_bf16 v[28:31], v[182:185], v[190:193], v[28:31]
	v_mfma_f32_16x16x32_bf16 v[24:27], v[182:185], v[202:205], v[24:27]
	s_waitcnt vmcnt(0)
	v_mfma_f32_16x16x32_bf16 v[28:31], v[206:209], v[214:217], v[28:31]
	v_mfma_f32_16x16x32_bf16 v[24:27], v[206:209], v[224:227], v[24:27]
	v_mfma_f32_16x16x32_bf16 v[28:31], v[210:213], v[220:223], v[28:31]
	v_mfma_f32_16x16x32_bf16 v[24:27], v[210:213], v[228:231], v[24:27]
	s_nop 4
	s_waitcnt lgkmcnt(0)
	v_pk_add_f32 v[52:53], v[54:55], v[56:57]
	s_nop 0
	v_pk_mul_f32 v[52:53], v[52:53], s[6:7] op_sel_hi:[1,0]
	s_nop 0
	v_fma_f32 v49, -v52, v52, v53
	v_max_f32_e32 v49, 0, v49
	v_add_f32_e32 v49, 0x3727c5ac, v49
	v_mul_f32_e32 v53, 0x4b800000, v49
	v_cmp_gt_f32_e64 s[22:23], s14, v49
	s_nop 1
	v_cndmask_b32_e64 v49, v49, v53, s[22:23]
	v_rsq_f32_e32 v49, v49
	v_add_u32_e32 v53, s4, v64
	v_lshl_add_u32 v53, s101, 11, v53
	ds_write_b128 v53, v[28:31]
	ds_write_b128 v53, v[24:27] offset:1024
	v_add_u32_e32 v23, s12, v64
	s_waitcnt lgkmcnt(0)
	s_barrier
	s_lshr_b32 s10, s12, 11
	s_cmp_lg_u32 s10, s101
	s_cbranch_scc1 .LBB0_1373
	ds_read_b128 v[8:11], v23
	ds_read_b128 v[12:15], v23 offset:8192
	v_mul_f32_e32 v16, 0x45800000, v49
	v_cndmask_b32_e64 v22, v49, v16, s[22:23]
	ds_read_b128 v[16:19], v23 offset:16384
	s_waitcnt lgkmcnt(2)
	v_pk_add_f32 v[10:11], v[10:11], 0 op_sel_hi:[1,0]
	v_pk_add_f32 v[20:21], v[8:9], 0 op_sel_hi:[1,0]
	s_waitcnt lgkmcnt(1)
	v_pk_add_f32 v[14:15], v[10:11], v[14:15]
	ds_read_b128 v[8:11], v23 offset:24576
	v_pk_add_f32 v[20:21], v[20:21], v[12:13]
	s_waitcnt lgkmcnt(1)
	v_pk_add_f32 v[18:19], v[14:15], v[18:19]
	ds_read_b128 v[12:15], v23 offset:32768
	v_pk_add_f32 v[16:17], v[20:21], v[16:17]
	s_waitcnt lgkmcnt(1)
	v_pk_add_f32 v[18:19], v[18:19], v[10:11]
	v_pk_add_f32 v[20:21], v[16:17], v[8:9]
	ds_read_b128 v[8:11], v23 offset:40960
	s_waitcnt lgkmcnt(1)
	v_pk_add_f32 v[24:25], v[18:19], v[14:15]
	ds_read_b128 v[14:17], v23 offset:49152
	v_pk_add_f32 v[12:13], v[20:21], v[12:13]
	ds_read_b128 v[18:21], v23 offset:57344
	s_waitcnt lgkmcnt(2)
	v_pk_add_f32 v[8:9], v[12:13], v[8:9]
	v_lshlrev_b32_e32 v12, 16, v60
	s_waitcnt lgkmcnt(1)
	v_pk_add_f32 v[8:9], v[8:9], v[14:15]
	v_and_b32_e32 v13, 0xffff0000, v60
	v_lshlrev_b32_e32 v14, 16, v61
	v_and_b32_e32 v15, 0xffff0000, v61
	v_pk_add_f32 v[10:11], v[24:25], v[10:11]
	v_sub_f32_e32 v13, v13, v52
	v_sub_f32_e32 v12, v12, v52
	v_sub_f32_e32 v15, v15, v52
	v_sub_f32_e32 v14, v14, v52
	v_pk_add_f32 v[10:11], v[10:11], v[16:17]
	v_pk_mul_f32 v[14:15], v[14:15], v[22:23] op_sel_hi:[1,0]
	v_pk_mul_f32 v[12:13], v[12:13], v[22:23] op_sel_hi:[1,0]
	s_waitcnt lgkmcnt(0)
	v_pk_add_f32 v[10:11], v[10:11], v[20:21]
	v_pk_add_f32 v[8:9], v[8:9], v[18:19]
	v_pk_fma_f32 v[0:1], v[0:1], v[12:13], v[4:5]
	v_pk_fma_f32 v[2:3], v[2:3], v[14:15], v[6:7]
	v_pk_fma_f32 v[6:7], v[0:1], s[70:71], v[8:9] op_sel_hi:[1,0,1]
	v_pk_fma_f32 v[4:5], v[2:3], s[70:71], v[10:11] op_sel_hi:[1,0,1]
	v_mul_f32_e32 v1, v6, v6
	v_mul_f32_e32 v3, v7, v7
	v_mul_f32_e32 v9, v4, v4
	v_mul_f32_e32 v11, v5, v5
	v_mov_b32_e32 v0, v6
	v_mov_b32_e32 v2, v7
	v_mov_b32_e32 v8, v4
	v_mov_b32_e32 v10, v5
	v_pk_add_f32 v[0:1], v[0:1], v[2:3]
	v_pk_add_f32 v[2:3], v[8:9], v[10:11]
	v_cvt_pk_bf16_f32 v6, v6, v7
	v_cvt_pk_bf16_f32 v7, v4, v5
	global_store_dwordx2 v[58:59], v[6:7], off
	v_pk_add_f32 v[0:1], v[0:1], v[2:3]
	ds_bpermute_b32 v2, v66, v0
	ds_bpermute_b32 v3, v66, v1
	s_waitcnt lgkmcnt(0)
	v_pk_add_f32 v[0:1], v[0:1], v[2:3]
	ds_bpermute_b32 v2, v67, v0
	ds_bpermute_b32 v3, v67, v1
	s_and_saveexec_b64 s[10:11], vcc
	s_cbranch_execz .LBB0_1373
	s_lshl_b32 s16, s100, 1
	s_ashr_i32 s17, s16, 31
	v_lshl_add_u64 v[4:5], s[16:17], 2, v[44:45]
	s_waitcnt lgkmcnt(0)
	v_pk_add_f32 v[0:1], v[0:1], v[2:3]
	global_store_dwordx2 v[4:5], v[0:1], off
	s_branch .LBB0_1373
